# pool item: the up-to-16 window-initialisation row loads issued together under their per-step lane masks, accumulated afterwards in the original order
# speedup vs baseline: 1.0018x; 1.0018x over previous
; #define OPAQUE_V(x) asm volatile("" : "+v"(x))
; __device__ __forceinline__ float bflo(unsigned w) { return __uint_as_float(w << 16); }
; __device__ __forceinline__ float bfhi(unsigned w) { return __uint_as_float(w & 0xffff0000u); }
; __device__ __forceinline__ void pool_item(KP p, int n) {
;     int tid_ = threadIdx.x; OPAQUE_V(tid_); const int tid = tid_;
;     const bf16_t* HM = (const bf16_t*)(p->ws + WS_HM);
;     bf16_t* MIX = (bf16_t*)(p->ws + WS_MIX);
;     const int c = (tid & 127) * 8, tq = tid >> 7, g = c >> 8, w = 2 << g;
;     const int ts = n * 128 + tq * 32;
;     float s[8];
; #pragma unroll
;     for (int i = 0; i < 8; ++i) s[i] = 0.f;
;     for (int tau = 1; tau <= w; ++tau) { const int tok = ts - tau; if (tok >= 0) { const u32x4 a = *(const u32x4*)(HM + (size_t)tok * HMW + C_AIN + c);
;             s[0] += bflo(a.x); s[1] += bfhi(a.x); s[2] += bflo(a.y); s[3] += bfhi(a.y); s[4] += bflo(a.z); s[5] += bfhi(a.z); s[6] += bflo(a.w); s[7] += bfhi(a.w); } }
; __device__ __forceinline__ void phase_mixers(KP p, LAS unsigned char* lds, int l) {
;     ...
;         const int it = __builtin_amdgcn_readfirstlane((int)qslot[0]);
;         if (it >= 832) break;
;         if (it < 64) {
;             unsigned char* ws = p->ws;
;             pg8::Gemm g{(const bf16_t*)(ws + WS_XB), (const bf16_t*)(ws + WS_WIN + l * SZ_WIN), SEQ, DIN, DM};
;             pg8::ExtraOrder S{it, DIN / 256 - 1};
;             pg8::EpiH E{(bf16_t*)(ws + WS_HM), (bf16_t*)(ws + WS_HG)};
;             pg8::gemm_phase<GEMM_ALIGN, GEMM_SP2>(lds, g, S, E);
;         }
;         else if (it < 192) sgu_item(p, lds, l, it - 64);
;         else if (it < 448) attn_item(p, lds, l, (it - 192) >> 1, (it - 192) & 1);
;         else if (it < 704) conv_item(p, lds, l, it - 448);
;         else pool_item(p, it - 704);
.LBB0_370:
	s_or_b64 exec, exec, s[40:41]
	v_mov_b32_e32 v0, s53
	s_waitcnt lgkmcnt(0)
	s_barrier
	ds_read_b32 v0, v0
	s_mov_b64 s[40:41], -1
	s_waitcnt lgkmcnt(0)
	v_readfirstlane_b32 s92, v0
	s_cmpk_gt_i32 s92, 0x33f
	s_cbranch_scc1 .LBB0_365
	s_cmp_gt_i32 s92, 63
	s_cbranch_scc0 .LBB0_541
	s_cmpk_gt_u32 s92, 0xbf
	s_cbranch_scc0 .LBB0_517
	s_cmpk_gt_u32 s92, 0x1bf
	s_cbranch_scc0 .LBB0_467
	s_cmpk_gt_u32 s92, 0x2bf
	s_cbranch_scc0 .LBB0_398
	v_mov_b32_e32 v3, v166
	s_lshl_b32 s6, s92, 7
	v_lshlrev_b32_e32 v0, 3, v3
	v_and_b32_e32 v2, 0x3f8, v0
	v_bfe_u32 v0, v0, 8, 2
	v_lshlrev_b32_e64 v80, v0, 2
	v_ashrrev_i32_e32 v0, 2, v3
	v_and_b32_e32 v4, 0xffffffe0, v0
	v_lshlrev_b32_e32 v0, 1, v2
	s_add_i32 s24, s6, 0xfffe9fff
	v_mov_b32_e32 v72, 0
	v_lshl_add_u64 v[66:67], s[36:37], 0, v[0:1]
	v_add_u32_e32 v0, s24, v4
	s_mov_b64 s[40:41], 0
	v_mov_b32_e32 v5, v80
	v_mov_b32_e32 v73, v72
	v_mov_b32_e32 v78, v72
	v_mov_b32_e32 v79, v72
	v_mov_b32_e32 v74, v72
	v_mov_b32_e32 v75, v72
	v_mov_b32_e32 v76, v72
	v_mov_b32_e32 v77, v72
	v_mov_b32_e32 v95, v0
	v_cmp_gt_u32_e64 s[44:45], v80, 0
	v_cmp_lt_i32_e32 vcc, -1, v95
	s_nop 1
	s_and_b64 vcc, vcc, s[44:45]
	s_and_saveexec_b64 s[42:43], vcc
	v_mad_u64_u32 v[6:7], s[24:25], v95, s50, v[66:67]
	global_load_dwordx4 v[96:99], v[6:7], off
	s_mov_b64 exec, s[42:43]
	v_add_u32_e32 v95, -1, v0
	v_cmp_gt_u32_e64 s[44:45], v80, 1
	v_cmp_lt_i32_e32 vcc, -1, v95
	s_nop 1
	s_and_b64 vcc, vcc, s[44:45]
	s_and_saveexec_b64 s[42:43], vcc
	v_mad_u64_u32 v[6:7], s[24:25], v95, s50, v[66:67]
	global_load_dwordx4 v[100:103], v[6:7], off
	s_mov_b64 exec, s[42:43]
	v_add_u32_e32 v95, -2, v0
	v_cmp_gt_u32_e64 s[44:45], v80, 2
	v_cmp_lt_i32_e32 vcc, -1, v95
	s_nop 1
	s_and_b64 vcc, vcc, s[44:45]
	s_and_saveexec_b64 s[42:43], vcc
	v_mad_u64_u32 v[6:7], s[24:25], v95, s50, v[66:67]
	global_load_dwordx4 v[104:107], v[6:7], off
	s_mov_b64 exec, s[42:43]
	v_add_u32_e32 v95, -3, v0
	v_cmp_gt_u32_e64 s[44:45], v80, 3
	v_cmp_lt_i32_e32 vcc, -1, v95
	s_nop 1
	s_and_b64 vcc, vcc, s[44:45]
	s_and_saveexec_b64 s[42:43], vcc
	v_mad_u64_u32 v[6:7], s[24:25], v95, s50, v[66:67]
	global_load_dwordx4 v[108:111], v[6:7], off
	s_mov_b64 exec, s[42:43]
	v_add_u32_e32 v95, -4, v0
	v_cmp_gt_u32_e64 s[44:45], v80, 4
	v_cmp_lt_i32_e32 vcc, -1, v95
	s_nop 1
	s_and_b64 vcc, vcc, s[44:45]
	s_and_saveexec_b64 s[42:43], vcc
	v_mad_u64_u32 v[6:7], s[24:25], v95, s50, v[66:67]
	global_load_dwordx4 v[112:115], v[6:7], off
	s_mov_b64 exec, s[42:43]
	v_add_u32_e32 v95, -5, v0
	v_cmp_gt_u32_e64 s[44:45], v80, 5
	v_cmp_lt_i32_e32 vcc, -1, v95
	s_nop 1
	s_and_b64 vcc, vcc, s[44:45]
	s_and_saveexec_b64 s[42:43], vcc
	v_mad_u64_u32 v[6:7], s[24:25], v95, s50, v[66:67]
	global_load_dwordx4 v[116:119], v[6:7], off
	s_mov_b64 exec, s[42:43]
	v_add_u32_e32 v95, -6, v0
	v_cmp_gt_u32_e64 s[44:45], v80, 6
	v_cmp_lt_i32_e32 vcc, -1, v95
	s_nop 1
	s_and_b64 vcc, vcc, s[44:45]
	s_and_saveexec_b64 s[42:43], vcc
	v_mad_u64_u32 v[6:7], s[24:25], v95, s50, v[66:67]
	global_load_dwordx4 v[120:123], v[6:7], off
	s_mov_b64 exec, s[42:43]
	v_add_u32_e32 v95, -7, v0
	v_cmp_gt_u32_e64 s[44:45], v80, 7
	v_cmp_lt_i32_e32 vcc, -1, v95
	s_nop 1
	s_and_b64 vcc, vcc, s[44:45]
	s_and_saveexec_b64 s[42:43], vcc
	v_mad_u64_u32 v[6:7], s[24:25], v95, s50, v[66:67]
	global_load_dwordx4 v[124:127], v[6:7], off
	s_mov_b64 exec, s[42:43]
	v_add_u32_e32 v95, -8, v0
	v_cmp_gt_u32_e64 s[44:45], v80, 8
	v_cmp_lt_i32_e32 vcc, -1, v95
	s_nop 1
	s_and_b64 vcc, vcc, s[44:45]
	s_and_saveexec_b64 s[42:43], vcc
	v_mad_u64_u32 v[6:7], s[24:25], v95, s50, v[66:67]
	global_load_dwordx4 v[128:131], v[6:7], off
	s_mov_b64 exec, s[42:43]
	v_add_u32_e32 v95, -9, v0
	v_cmp_gt_u32_e64 s[44:45], v80, 9
	v_cmp_lt_i32_e32 vcc, -1, v95
	s_nop 1
	s_and_b64 vcc, vcc, s[44:45]
	s_and_saveexec_b64 s[42:43], vcc
	v_mad_u64_u32 v[6:7], s[24:25], v95, s50, v[66:67]
	global_load_dwordx4 v[132:135], v[6:7], off
	s_mov_b64 exec, s[42:43]
	v_add_u32_e32 v95, -10, v0
	v_cmp_gt_u32_e64 s[44:45], v80, 10
	v_cmp_lt_i32_e32 vcc, -1, v95
	s_nop 1
	s_and_b64 vcc, vcc, s[44:45]
	s_and_saveexec_b64 s[42:43], vcc
	v_mad_u64_u32 v[6:7], s[24:25], v95, s50, v[66:67]
	global_load_dwordx4 v[136:139], v[6:7], off
	s_mov_b64 exec, s[42:43]
	v_add_u32_e32 v95, -11, v0
	v_cmp_gt_u32_e64 s[44:45], v80, 11
	v_cmp_lt_i32_e32 vcc, -1, v95
	s_nop 1
	s_and_b64 vcc, vcc, s[44:45]
	s_and_saveexec_b64 s[42:43], vcc
	v_mad_u64_u32 v[6:7], s[24:25], v95, s50, v[66:67]
	global_load_dwordx4 v[174:177], v[6:7], off
	s_mov_b64 exec, s[42:43]
	v_add_u32_e32 v95, -12, v0
	v_cmp_gt_u32_e64 s[44:45], v80, 12
	v_cmp_lt_i32_e32 vcc, -1, v95
	s_nop 1
	s_and_b64 vcc, vcc, s[44:45]
	s_and_saveexec_b64 s[42:43], vcc
	v_mad_u64_u32 v[6:7], s[24:25], v95, s50, v[66:67]
	global_load_dwordx4 v[178:181], v[6:7], off
	s_mov_b64 exec, s[42:43]
	v_add_u32_e32 v95, -13, v0
	v_cmp_gt_u32_e64 s[44:45], v80, 13
	v_cmp_lt_i32_e32 vcc, -1, v95
	s_nop 1
	s_and_b64 vcc, vcc, s[44:45]
	s_and_saveexec_b64 s[42:43], vcc
	v_mad_u64_u32 v[6:7], s[24:25], v95, s50, v[66:67]
	global_load_dwordx4 v[182:185], v[6:7], off
	s_mov_b64 exec, s[42:43]
	v_add_u32_e32 v95, -14, v0
	v_cmp_gt_u32_e64 s[44:45], v80, 14
	v_cmp_lt_i32_e32 vcc, -1, v95
	s_nop 1
	s_and_b64 vcc, vcc, s[44:45]
	s_and_saveexec_b64 s[42:43], vcc
	v_mad_u64_u32 v[6:7], s[24:25], v95, s50, v[66:67]
	global_load_dwordx4 v[186:189], v[6:7], off
	s_mov_b64 exec, s[42:43]
	v_add_u32_e32 v95, -15, v0
	v_cmp_gt_u32_e64 s[44:45], v80, 15
	v_cmp_lt_i32_e32 vcc, -1, v95
	s_nop 1
	s_and_b64 vcc, vcc, s[44:45]
	s_and_saveexec_b64 s[42:43], vcc
	v_mad_u64_u32 v[6:7], s[24:25], v95, s50, v[66:67]
	global_load_dwordx4 v[190:193], v[6:7], off
	s_mov_b64 exec, s[42:43]
	s_waitcnt vmcnt(0)
; __device__ __forceinline__ float bflo(unsigned w) { return __uint_as_float(w << 16); }
; __device__ __forceinline__ float bfhi(unsigned w) { return __uint_as_float(w & 0xffff0000u); }
; __device__ __forceinline__ void pool_item(KP p, int n) {
;     ...
;     for (int tau = 1; tau <= w; ++tau) { const int tok = ts - tau; if (tok >= 0) { const u32x4 a = *(const u32x4*)(HM + (size_t)tok * HMW + C_AIN + c);
;             s[0] += bflo(a.x); s[1] += bfhi(a.x); s[2] += bflo(a.y); s[3] += bfhi(a.y); s[4] += bflo(a.z); s[5] += bfhi(a.z); s[6] += bflo(a.w); s[7] += bfhi(a.w); } }
	v_mov_b32_e32 v95, v0
	v_cmp_gt_u32_e64 s[44:45], v80, 0
	v_cmp_lt_i32_e32 vcc, -1, v95
	s_nop 1
	s_and_b64 vcc, vcc, s[44:45]
	s_and_saveexec_b64 s[42:43], vcc
	v_lshlrev_b32_e32 v10, 16, v96
	v_and_b32_e32 v11, 0xffff0000, v96
	v_lshlrev_b32_e32 v6, 16, v97
	v_and_b32_e32 v7, 0xffff0000, v97
	v_pk_add_f32 v[78:79], v[78:79], v[6:7]
	v_lshlrev_b32_e32 v6, 16, v98
	v_and_b32_e32 v7, 0xffff0000, v98
	v_pk_add_f32 v[74:75], v[74:75], v[6:7]
	v_lshlrev_b32_e32 v6, 16, v99
	v_and_b32_e32 v7, 0xffff0000, v99
	v_pk_add_f32 v[72:73], v[72:73], v[10:11]
	v_pk_add_f32 v[76:77], v[76:77], v[6:7]
	s_mov_b64 exec, s[42:43]
	v_add_u32_e32 v95, -1, v0
	v_cmp_gt_u32_e64 s[44:45], v80, 1
	v_cmp_lt_i32_e32 vcc, -1, v95
	s_nop 1
	s_and_b64 vcc, vcc, s[44:45]
	s_and_saveexec_b64 s[42:43], vcc
	v_lshlrev_b32_e32 v10, 16, v100
	v_and_b32_e32 v11, 0xffff0000, v100
	v_lshlrev_b32_e32 v6, 16, v101
	v_and_b32_e32 v7, 0xffff0000, v101
	v_pk_add_f32 v[78:79], v[78:79], v[6:7]
	v_lshlrev_b32_e32 v6, 16, v102
	v_and_b32_e32 v7, 0xffff0000, v102
	v_pk_add_f32 v[74:75], v[74:75], v[6:7]
	v_lshlrev_b32_e32 v6, 16, v103
	v_and_b32_e32 v7, 0xffff0000, v103
	v_pk_add_f32 v[72:73], v[72:73], v[10:11]
	v_pk_add_f32 v[76:77], v[76:77], v[6:7]
	s_mov_b64 exec, s[42:43]
	v_add_u32_e32 v95, -2, v0
	v_cmp_gt_u32_e64 s[44:45], v80, 2
	v_cmp_lt_i32_e32 vcc, -1, v95
	s_nop 1
	s_and_b64 vcc, vcc, s[44:45]
	s_and_saveexec_b64 s[42:43], vcc
	v_lshlrev_b32_e32 v10, 16, v104
	v_and_b32_e32 v11, 0xffff0000, v104
	v_lshlrev_b32_e32 v6, 16, v105
	v_and_b32_e32 v7, 0xffff0000, v105
	v_pk_add_f32 v[78:79], v[78:79], v[6:7]
	v_lshlrev_b32_e32 v6, 16, v106
	v_and_b32_e32 v7, 0xffff0000, v106
	v_pk_add_f32 v[74:75], v[74:75], v[6:7]
	v_lshlrev_b32_e32 v6, 16, v107
	v_and_b32_e32 v7, 0xffff0000, v107
	v_pk_add_f32 v[72:73], v[72:73], v[10:11]
	v_pk_add_f32 v[76:77], v[76:77], v[6:7]
	s_mov_b64 exec, s[42:43]
	v_add_u32_e32 v95, -3, v0
	v_cmp_gt_u32_e64 s[44:45], v80, 3
	v_cmp_lt_i32_e32 vcc, -1, v95
	s_nop 1
	s_and_b64 vcc, vcc, s[44:45]
	s_and_saveexec_b64 s[42:43], vcc
	v_lshlrev_b32_e32 v10, 16, v108
	v_and_b32_e32 v11, 0xffff0000, v108
	v_lshlrev_b32_e32 v6, 16, v109
	v_and_b32_e32 v7, 0xffff0000, v109
	v_pk_add_f32 v[78:79], v[78:79], v[6:7]
	v_lshlrev_b32_e32 v6, 16, v110
	v_and_b32_e32 v7, 0xffff0000, v110
	v_pk_add_f32 v[74:75], v[74:75], v[6:7]
	v_lshlrev_b32_e32 v6, 16, v111
	v_and_b32_e32 v7, 0xffff0000, v111
	v_pk_add_f32 v[72:73], v[72:73], v[10:11]
	v_pk_add_f32 v[76:77], v[76:77], v[6:7]
	s_mov_b64 exec, s[42:43]
	v_add_u32_e32 v95, -4, v0
	v_cmp_gt_u32_e64 s[44:45], v80, 4
	v_cmp_lt_i32_e32 vcc, -1, v95
	s_nop 1
	s_and_b64 vcc, vcc, s[44:45]
	s_and_saveexec_b64 s[42:43], vcc
	v_lshlrev_b32_e32 v10, 16, v112
	v_and_b32_e32 v11, 0xffff0000, v112
	v_lshlrev_b32_e32 v6, 16, v113
	v_and_b32_e32 v7, 0xffff0000, v113
	v_pk_add_f32 v[78:79], v[78:79], v[6:7]
	v_lshlrev_b32_e32 v6, 16, v114
	v_and_b32_e32 v7, 0xffff0000, v114
	v_pk_add_f32 v[74:75], v[74:75], v[6:7]
	v_lshlrev_b32_e32 v6, 16, v115
	v_and_b32_e32 v7, 0xffff0000, v115
	v_pk_add_f32 v[72:73], v[72:73], v[10:11]
	v_pk_add_f32 v[76:77], v[76:77], v[6:7]
	s_mov_b64 exec, s[42:43]
	v_add_u32_e32 v95, -5, v0
	v_cmp_gt_u32_e64 s[44:45], v80, 5
	v_cmp_lt_i32_e32 vcc, -1, v95
	s_nop 1
	s_and_b64 vcc, vcc, s[44:45]
	s_and_saveexec_b64 s[42:43], vcc
	v_lshlrev_b32_e32 v10, 16, v116
	v_and_b32_e32 v11, 0xffff0000, v116
	v_lshlrev_b32_e32 v6, 16, v117
	v_and_b32_e32 v7, 0xffff0000, v117
	v_pk_add_f32 v[78:79], v[78:79], v[6:7]
	v_lshlrev_b32_e32 v6, 16, v118
	v_and_b32_e32 v7, 0xffff0000, v118
	v_pk_add_f32 v[74:75], v[74:75], v[6:7]
	v_lshlrev_b32_e32 v6, 16, v119
	v_and_b32_e32 v7, 0xffff0000, v119
	v_pk_add_f32 v[72:73], v[72:73], v[10:11]
	v_pk_add_f32 v[76:77], v[76:77], v[6:7]
	s_mov_b64 exec, s[42:43]
	v_add_u32_e32 v95, -6, v0
	v_cmp_gt_u32_e64 s[44:45], v80, 6
	v_cmp_lt_i32_e32 vcc, -1, v95
	s_nop 1
	s_and_b64 vcc, vcc, s[44:45]
	s_and_saveexec_b64 s[42:43], vcc
	v_lshlrev_b32_e32 v10, 16, v120
	v_and_b32_e32 v11, 0xffff0000, v120
	v_lshlrev_b32_e32 v6, 16, v121
	v_and_b32_e32 v7, 0xffff0000, v121
	v_pk_add_f32 v[78:79], v[78:79], v[6:7]
	v_lshlrev_b32_e32 v6, 16, v122
	v_and_b32_e32 v7, 0xffff0000, v122
	v_pk_add_f32 v[74:75], v[74:75], v[6:7]
	v_lshlrev_b32_e32 v6, 16, v123
	v_and_b32_e32 v7, 0xffff0000, v123
	v_pk_add_f32 v[72:73], v[72:73], v[10:11]
	v_pk_add_f32 v[76:77], v[76:77], v[6:7]
	s_mov_b64 exec, s[42:43]
	v_add_u32_e32 v95, -7, v0
	v_cmp_gt_u32_e64 s[44:45], v80, 7
	v_cmp_lt_i32_e32 vcc, -1, v95
	s_nop 1
	s_and_b64 vcc, vcc, s[44:45]
	s_and_saveexec_b64 s[42:43], vcc
	v_lshlrev_b32_e32 v10, 16, v124
	v_and_b32_e32 v11, 0xffff0000, v124
	v_lshlrev_b32_e32 v6, 16, v125
	v_and_b32_e32 v7, 0xffff0000, v125
	v_pk_add_f32 v[78:79], v[78:79], v[6:7]
	v_lshlrev_b32_e32 v6, 16, v126
	v_and_b32_e32 v7, 0xffff0000, v126
	v_pk_add_f32 v[74:75], v[74:75], v[6:7]
	v_lshlrev_b32_e32 v6, 16, v127
	v_and_b32_e32 v7, 0xffff0000, v127
	v_pk_add_f32 v[72:73], v[72:73], v[10:11]
	v_pk_add_f32 v[76:77], v[76:77], v[6:7]
	s_mov_b64 exec, s[42:43]
; __device__ __forceinline__ float bflo(unsigned w) { return __uint_as_float(w << 16); }
; __device__ __forceinline__ float bfhi(unsigned w) { return __uint_as_float(w & 0xffff0000u); }
; __device__ __forceinline__ void pool_item(KP p, int n) {
;     ...
;     for (int tau = 1; tau <= w; ++tau) { const int tok = ts - tau; if (tok >= 0) { const u32x4 a = *(const u32x4*)(HM + (size_t)tok * HMW + C_AIN + c);
;             s[0] += bflo(a.x); s[1] += bfhi(a.x); s[2] += bflo(a.y); s[3] += bfhi(a.y); s[4] += bflo(a.z); s[5] += bfhi(a.z); s[6] += bflo(a.w); s[7] += bfhi(a.w); } }
	v_add_u32_e32 v95, -8, v0
	v_cmp_gt_u32_e64 s[44:45], v80, 8
	v_cmp_lt_i32_e32 vcc, -1, v95
	s_nop 1
	s_and_b64 vcc, vcc, s[44:45]
	s_and_saveexec_b64 s[42:43], vcc
	v_lshlrev_b32_e32 v10, 16, v128
	v_and_b32_e32 v11, 0xffff0000, v128
	v_lshlrev_b32_e32 v6, 16, v129
	v_and_b32_e32 v7, 0xffff0000, v129
	v_pk_add_f32 v[78:79], v[78:79], v[6:7]
	v_lshlrev_b32_e32 v6, 16, v130
	v_and_b32_e32 v7, 0xffff0000, v130
	v_pk_add_f32 v[74:75], v[74:75], v[6:7]
	v_lshlrev_b32_e32 v6, 16, v131
	v_and_b32_e32 v7, 0xffff0000, v131
	v_pk_add_f32 v[72:73], v[72:73], v[10:11]
	v_pk_add_f32 v[76:77], v[76:77], v[6:7]
	s_mov_b64 exec, s[42:43]
	v_add_u32_e32 v95, -9, v0
	v_cmp_gt_u32_e64 s[44:45], v80, 9
	v_cmp_lt_i32_e32 vcc, -1, v95
	s_nop 1
	s_and_b64 vcc, vcc, s[44:45]
	s_and_saveexec_b64 s[42:43], vcc
	v_lshlrev_b32_e32 v10, 16, v132
	v_and_b32_e32 v11, 0xffff0000, v132
	v_lshlrev_b32_e32 v6, 16, v133
	v_and_b32_e32 v7, 0xffff0000, v133
	v_pk_add_f32 v[78:79], v[78:79], v[6:7]
	v_lshlrev_b32_e32 v6, 16, v134
	v_and_b32_e32 v7, 0xffff0000, v134
	v_pk_add_f32 v[74:75], v[74:75], v[6:7]
	v_lshlrev_b32_e32 v6, 16, v135
	v_and_b32_e32 v7, 0xffff0000, v135
	v_pk_add_f32 v[72:73], v[72:73], v[10:11]
	v_pk_add_f32 v[76:77], v[76:77], v[6:7]
	s_mov_b64 exec, s[42:43]
	v_add_u32_e32 v95, -10, v0
	v_cmp_gt_u32_e64 s[44:45], v80, 10
	v_cmp_lt_i32_e32 vcc, -1, v95
	s_nop 1
	s_and_b64 vcc, vcc, s[44:45]
	s_and_saveexec_b64 s[42:43], vcc
	v_lshlrev_b32_e32 v10, 16, v136
	v_and_b32_e32 v11, 0xffff0000, v136
	v_lshlrev_b32_e32 v6, 16, v137
	v_and_b32_e32 v7, 0xffff0000, v137
	v_pk_add_f32 v[78:79], v[78:79], v[6:7]
	v_lshlrev_b32_e32 v6, 16, v138
	v_and_b32_e32 v7, 0xffff0000, v138
	v_pk_add_f32 v[74:75], v[74:75], v[6:7]
	v_lshlrev_b32_e32 v6, 16, v139
	v_and_b32_e32 v7, 0xffff0000, v139
	v_pk_add_f32 v[72:73], v[72:73], v[10:11]
	v_pk_add_f32 v[76:77], v[76:77], v[6:7]
	s_mov_b64 exec, s[42:43]
	v_add_u32_e32 v95, -11, v0
	v_cmp_gt_u32_e64 s[44:45], v80, 11
	v_cmp_lt_i32_e32 vcc, -1, v95
	s_nop 1
	s_and_b64 vcc, vcc, s[44:45]
	s_and_saveexec_b64 s[42:43], vcc
	v_lshlrev_b32_e32 v10, 16, v174
	v_and_b32_e32 v11, 0xffff0000, v174
	v_lshlrev_b32_e32 v6, 16, v175
	v_and_b32_e32 v7, 0xffff0000, v175
	v_pk_add_f32 v[78:79], v[78:79], v[6:7]
	v_lshlrev_b32_e32 v6, 16, v176
	v_and_b32_e32 v7, 0xffff0000, v176
	v_pk_add_f32 v[74:75], v[74:75], v[6:7]
	v_lshlrev_b32_e32 v6, 16, v177
	v_and_b32_e32 v7, 0xffff0000, v177
	v_pk_add_f32 v[72:73], v[72:73], v[10:11]
	v_pk_add_f32 v[76:77], v[76:77], v[6:7]
	s_mov_b64 exec, s[42:43]
	v_add_u32_e32 v95, -12, v0
	v_cmp_gt_u32_e64 s[44:45], v80, 12
	v_cmp_lt_i32_e32 vcc, -1, v95
	s_nop 1
	s_and_b64 vcc, vcc, s[44:45]
	s_and_saveexec_b64 s[42:43], vcc
	v_lshlrev_b32_e32 v10, 16, v178
	v_and_b32_e32 v11, 0xffff0000, v178
	v_lshlrev_b32_e32 v6, 16, v179
	v_and_b32_e32 v7, 0xffff0000, v179
	v_pk_add_f32 v[78:79], v[78:79], v[6:7]
	v_lshlrev_b32_e32 v6, 16, v180
	v_and_b32_e32 v7, 0xffff0000, v180
	v_pk_add_f32 v[74:75], v[74:75], v[6:7]
	v_lshlrev_b32_e32 v6, 16, v181
	v_and_b32_e32 v7, 0xffff0000, v181
	v_pk_add_f32 v[72:73], v[72:73], v[10:11]
	v_pk_add_f32 v[76:77], v[76:77], v[6:7]
	s_mov_b64 exec, s[42:43]
	v_add_u32_e32 v95, -13, v0
	v_cmp_gt_u32_e64 s[44:45], v80, 13
	v_cmp_lt_i32_e32 vcc, -1, v95
	s_nop 1
	s_and_b64 vcc, vcc, s[44:45]
	s_and_saveexec_b64 s[42:43], vcc
	v_lshlrev_b32_e32 v10, 16, v182
	v_and_b32_e32 v11, 0xffff0000, v182
	v_lshlrev_b32_e32 v6, 16, v183
	v_and_b32_e32 v7, 0xffff0000, v183
	v_pk_add_f32 v[78:79], v[78:79], v[6:7]
	v_lshlrev_b32_e32 v6, 16, v184
	v_and_b32_e32 v7, 0xffff0000, v184
	v_pk_add_f32 v[74:75], v[74:75], v[6:7]
	v_lshlrev_b32_e32 v6, 16, v185
	v_and_b32_e32 v7, 0xffff0000, v185
	v_pk_add_f32 v[72:73], v[72:73], v[10:11]
	v_pk_add_f32 v[76:77], v[76:77], v[6:7]
	s_mov_b64 exec, s[42:43]
	v_add_u32_e32 v95, -14, v0
	v_cmp_gt_u32_e64 s[44:45], v80, 14
	v_cmp_lt_i32_e32 vcc, -1, v95
	s_nop 1
	s_and_b64 vcc, vcc, s[44:45]
	s_and_saveexec_b64 s[42:43], vcc
	v_lshlrev_b32_e32 v10, 16, v186
	v_and_b32_e32 v11, 0xffff0000, v186
	v_lshlrev_b32_e32 v6, 16, v187
	v_and_b32_e32 v7, 0xffff0000, v187
	v_pk_add_f32 v[78:79], v[78:79], v[6:7]
	v_lshlrev_b32_e32 v6, 16, v188
	v_and_b32_e32 v7, 0xffff0000, v188
	v_pk_add_f32 v[74:75], v[74:75], v[6:7]
	v_lshlrev_b32_e32 v6, 16, v189
	v_and_b32_e32 v7, 0xffff0000, v189
	v_pk_add_f32 v[72:73], v[72:73], v[10:11]
	v_pk_add_f32 v[76:77], v[76:77], v[6:7]
	s_mov_b64 exec, s[42:43]
	v_add_u32_e32 v95, -15, v0
	v_cmp_gt_u32_e64 s[44:45], v80, 15
	v_cmp_lt_i32_e32 vcc, -1, v95
	s_nop 1
	s_and_b64 vcc, vcc, s[44:45]
	s_and_saveexec_b64 s[42:43], vcc
	v_lshlrev_b32_e32 v10, 16, v190
	v_and_b32_e32 v11, 0xffff0000, v190
	v_lshlrev_b32_e32 v6, 16, v191
	v_and_b32_e32 v7, 0xffff0000, v191
	v_pk_add_f32 v[78:79], v[78:79], v[6:7]
	v_lshlrev_b32_e32 v6, 16, v192
	v_and_b32_e32 v7, 0xffff0000, v192
	v_pk_add_f32 v[74:75], v[74:75], v[6:7]
	v_lshlrev_b32_e32 v6, 16, v193
	v_and_b32_e32 v7, 0xffff0000, v193
	v_pk_add_f32 v[72:73], v[72:73], v[10:11]
	v_pk_add_f32 v[76:77], v[76:77], v[6:7]
	s_mov_b64 exec, s[42:43]
